# w_in GEMM epilogue rotary-key chunk: the 16 rope-table entries fetched up front instead of 16 serialized load+vmcnt(0) round trips
# baseline (speedup 1.0000x reference)
.LBB0_564:
	s_andn2_saveexec_b64 s[46:47], s[12:13]
	s_cbranch_execz .LBB0_630
	v_add_u32_e32 v70, 0xfffffd00, v128
	v_cndmask_b32_e64 v68, 0, 1, s[42:43]
	v_cmp_eq_u32_e64 s[12:13], 0, v70
	v_cmp_ne_u32_e64 s[14:15], 1, v68
	s_and_b64 vcc, exec, s[42:43]
	s_cbranch_vccnz .Lgi_rp_skip
	v_lshlrev_b32_e32 v226, 2, v160
	v_bfe_u32 v227, v79, 6, 6
	v_cndmask_b32_e64 v228, v151, v227, s[12:13]
	v_lshl_or_b32 v228, v228, 7, v226
	global_load_dwordx2 v[194:195], v228, s[36:37]
	v_cndmask_b32_e64 v229, v159, v227, s[12:13]
	v_lshl_or_b32 v229, v229, 7, v226
	global_load_dwordx2 v[196:197], v229, s[36:37]
	v_cndmask_b32_e64 v228, v157, v227, s[12:13]
	v_lshl_or_b32 v228, v228, 7, v226
	global_load_dwordx2 v[198:199], v228, s[36:37]
	v_cndmask_b32_e64 v229, v156, v227, s[12:13]
	v_lshl_or_b32 v229, v229, 7, v226
	global_load_dwordx2 v[200:201], v229, s[36:37]
	v_cndmask_b32_e64 v228, v155, v227, s[12:13]
	v_lshl_or_b32 v228, v228, 7, v226
	global_load_dwordx2 v[202:203], v228, s[36:37]
	v_cndmask_b32_e64 v229, v154, v227, s[12:13]
	v_lshl_or_b32 v229, v229, 7, v226
	global_load_dwordx2 v[204:205], v229, s[36:37]
	v_cndmask_b32_e64 v228, v153, v227, s[12:13]
	v_lshl_or_b32 v228, v228, 7, v226
	global_load_dwordx2 v[206:207], v228, s[36:37]
	v_cndmask_b32_e64 v229, v152, v227, s[12:13]
	v_lshl_or_b32 v229, v229, 7, v226
	global_load_dwordx2 v[208:209], v229, s[36:37]
	v_cndmask_b32_e64 v228, v150, v227, s[12:13]
	v_lshl_or_b32 v228, v228, 7, v226
	global_load_dwordx2 v[210:211], v228, s[36:37]
	v_cndmask_b32_e64 v229, v149, v227, s[12:13]
	v_lshl_or_b32 v229, v229, 7, v226
	global_load_dwordx2 v[212:213], v229, s[36:37]
	v_cndmask_b32_e64 v228, v148, v227, s[12:13]
	v_lshl_or_b32 v228, v228, 7, v226
	global_load_dwordx2 v[214:215], v228, s[36:37]
	v_cndmask_b32_e64 v229, v147, v227, s[12:13]
	v_lshl_or_b32 v229, v229, 7, v226
	global_load_dwordx2 v[216:217], v229, s[36:37]
	v_cndmask_b32_e64 v228, v146, v227, s[12:13]
	v_lshl_or_b32 v228, v228, 7, v226
	global_load_dwordx2 v[218:219], v228, s[36:37]
	v_cndmask_b32_e64 v229, v145, v227, s[12:13]
	v_lshl_or_b32 v229, v229, 7, v226
	global_load_dwordx2 v[220:221], v229, s[36:37]
	v_cndmask_b32_e64 v228, v144, v227, s[12:13]
	v_lshl_or_b32 v228, v228, 7, v226
	global_load_dwordx2 v[222:223], v228, s[36:37]
	v_cndmask_b32_e64 v229, v135, v227, s[12:13]
	v_lshl_or_b32 v229, v229, 7, v226
	global_load_dwordx2 v[224:225], v229, s[36:37]
.Lgi_rp_skip:
	s_andn2_b64 vcc, exec, s[42:43]
	s_mov_b64 s[0:1], -1
	s_cbranch_vccnz .LBB0_567
	v_and_b32_e32 v72, 0xcc, v79
	s_mov_b64 s[0:1], 0
	v_mov_b32_e32 v75, v60
	v_mov_b32_e32 v74, v56
.LBB0_567:
	v_ashrrev_i32_e32 v68, 12, v67
	v_lshlrev_b32_e32 v67, 2, v160
	s_andn2_b64 vcc, exec, s[0:1]
	v_mov_b64_e32 v[76:77], v[66:67]
	s_cbranch_vccnz .LBB0_569
	v_bfe_u32 v71, v79, 6, 6
	v_cndmask_b32_e64 v71, v151, v71, s[12:13]
	v_lshl_or_b32 v71, v71, 7, v67
	v_and_b32_e32 v71, 0xfcc, v79
	v_add_u32_e32 v72, 0x100, v71
	s_waitcnt vmcnt(15)
	v_mov_b32_e32 v74, v194
	v_mov_b32_e32 v75, v195
	v_pk_mul_f32 v[76:77], v[56:57], v[74:75] op_sel_hi:[0,1]
	v_pk_mul_f32 v[80:81], v[60:61], v[74:75] op_sel:[0,1] op_sel_hi:[1,0]
	v_pk_fma_f32 v[74:75], v[60:61], v[74:75], v[76:77] op_sel:[0,1,0] op_sel_hi:[0,0,1] neg_lo:[0,0,1] neg_hi:[0,0,1]
	v_add_f32_e32 v74, v80, v76
	v_mov_b64_e32 v[76:77], v[68:69]

.LBB0_571:
	s_andn2_b64 vcc, exec, s[0:1]
	v_mov_b64_e32 v[74:75], v[66:67]
	s_cbranch_vccnz .LBB0_573
	v_bfe_u32 v72, v73, 6, 6
	v_cndmask_b32_e64 v72, v159, v72, s[12:13]
	v_lshl_or_b32 v72, v72, 7, v67
	v_and_b32_e32 v72, 0xfcd, v73
	v_add_u32_e32 v72, 0x100, v72
	s_waitcnt vmcnt(16)
	v_mov_b32_e32 v74, v196
	v_mov_b32_e32 v75, v197
	v_pk_mul_f32 v[56:57], v[56:57], v[74:75] op_sel:[1,0]
	v_pk_mul_f32 v[76:77], v[60:61], v[74:75] op_sel:[1,1] op_sel_hi:[1,0]
	v_pk_fma_f32 v[60:61], v[60:61], v[74:75], v[56:57] op_sel:[1,1,0] op_sel_hi:[1,0,1] neg_lo:[0,0,1] neg_hi:[0,0,1]
	v_add_f32_e32 v57, v76, v56
	v_mov_b64_e32 v[74:75], v[68:69]

.LBB0_575:
	s_andn2_b64 vcc, exec, s[0:1]
	v_mov_b64_e32 v[60:61], v[66:67]
	s_cbranch_vccnz .LBB0_577
	v_bfe_u32 v56, v57, 6, 6
	v_cndmask_b32_e64 v56, v157, v56, s[12:13]
	v_lshl_or_b32 v56, v56, 7, v67
	v_and_b32_e32 v56, 0xfce, v57
	v_add_u32_e32 v56, 0x100, v56
	s_waitcnt vmcnt(17)
	v_mov_b32_e32 v60, v198
	v_mov_b32_e32 v61, v199
	v_pk_mul_f32 v[72:73], v[58:59], v[60:61] op_sel_hi:[0,1]
	v_pk_mul_f32 v[74:75], v[62:63], v[60:61] op_sel:[0,1] op_sel_hi:[1,0]
	v_pk_fma_f32 v[76:77], v[62:63], v[60:61], v[72:73] op_sel:[0,1,0] op_sel_hi:[0,0,1] neg_lo:[0,0,1] neg_hi:[0,0,1]
	v_add_f32_e32 v58, v74, v72
	v_mov_b64_e32 v[60:61], v[68:69]
	v_mov_b32_e32 v62, v77

.LBB0_579:
	s_andn2_b64 vcc, exec, s[0:1]
	v_mov_b64_e32 v[60:61], v[66:67]
	s_cbranch_vccnz .LBB0_581
	v_bfe_u32 v56, v57, 6, 6
	v_cndmask_b32_e64 v56, v156, v56, s[12:13]
	v_lshl_or_b32 v56, v56, 7, v67
	v_mov_b32_e32 v58, v59
	v_mov_b32_e32 v62, v63
	v_and_b32_e32 v56, 0xfcf, v57
	v_add_u32_e32 v56, 0x100, v56
	s_waitcnt vmcnt(18)
	v_mov_b32_e32 v60, v200
	v_mov_b32_e32 v61, v201
	v_pk_mul_f32 v[58:59], v[58:59], v[60:61] op_sel_hi:[0,1]
	v_pk_mul_f32 v[72:73], v[62:63], v[60:61] op_sel:[0,1] op_sel_hi:[0,0]
	v_pk_fma_f32 v[62:63], v[62:63], v[60:61], v[58:59] op_sel:[0,1,0] op_sel_hi:[0,0,1] neg_lo:[0,0,1] neg_hi:[0,0,1]
	v_add_f32_e32 v59, v72, v58
	v_mov_b64_e32 v[60:61], v[68:69]

.LBB0_583:
	s_andn2_b64 vcc, exec, s[0:1]
	v_mov_b64_e32 v[60:61], v[66:67]
	s_cbranch_vccnz .LBB0_585
	v_bfe_u32 v56, v57, 6, 6
	v_cndmask_b32_e64 v56, v155, v56, s[12:13]
	v_lshl_or_b32 v56, v56, 7, v67
	v_and_b32_e32 v56, 0xfdc, v57
	v_add_u32_e32 v56, 0x100, v56
	s_waitcnt vmcnt(19)
	v_mov_b32_e32 v58, v202
	v_mov_b32_e32 v59, v203
	v_pk_mul_f32 v[60:61], v[48:49], v[58:59] op_sel_hi:[0,1]
	v_pk_mul_f32 v[62:63], v[52:53], v[58:59] op_sel:[0,1] op_sel_hi:[1,0]
	v_pk_fma_f32 v[58:59], v[52:53], v[58:59], v[60:61] op_sel:[0,1,0] op_sel_hi:[0,0,1] neg_lo:[0,0,1] neg_hi:[0,0,1]
	v_add_f32_e32 v58, v62, v60
	v_mov_b64_e32 v[60:61], v[68:69]

.LBB0_587:
	s_andn2_b64 vcc, exec, s[0:1]
	v_mov_b64_e32 v[58:59], v[66:67]
	s_cbranch_vccnz .LBB0_589
	v_bfe_u32 v56, v57, 6, 6
	v_cndmask_b32_e64 v56, v154, v56, s[12:13]
	v_lshl_or_b32 v56, v56, 7, v67
	v_and_b32_e32 v56, 0xfdd, v57
	v_add_u32_e32 v56, 0x100, v56
	s_waitcnt vmcnt(20)
	v_mov_b32_e32 v58, v204
	v_mov_b32_e32 v59, v205
	v_pk_mul_f32 v[48:49], v[48:49], v[58:59] op_sel:[1,0]
	v_pk_mul_f32 v[60:61], v[52:53], v[58:59] op_sel:[1,1] op_sel_hi:[1,0]
	v_pk_fma_f32 v[52:53], v[52:53], v[58:59], v[48:49] op_sel:[1,1,0] op_sel_hi:[1,0,1] neg_lo:[0,0,1] neg_hi:[0,0,1]
	v_add_f32_e32 v49, v60, v48
	v_mov_b64_e32 v[58:59], v[68:69]

.LBB0_591:
	s_andn2_b64 vcc, exec, s[0:1]
	v_mov_b64_e32 v[52:53], v[66:67]
	s_cbranch_vccnz .LBB0_593
	v_bfe_u32 v48, v49, 6, 6
	v_cndmask_b32_e64 v48, v153, v48, s[12:13]
	v_lshl_or_b32 v48, v48, 7, v67
	v_and_b32_e32 v48, 0xfde, v49
	v_add_u32_e32 v48, 0x100, v48
	s_waitcnt vmcnt(21)
	v_mov_b32_e32 v52, v206
	v_mov_b32_e32 v53, v207
	v_pk_mul_f32 v[56:57], v[50:51], v[52:53] op_sel_hi:[0,1]
	v_pk_mul_f32 v[58:59], v[54:55], v[52:53] op_sel:[0,1] op_sel_hi:[1,0]
	v_pk_fma_f32 v[60:61], v[54:55], v[52:53], v[56:57] op_sel:[0,1,0] op_sel_hi:[0,0,1] neg_lo:[0,0,1] neg_hi:[0,0,1]
	v_add_f32_e32 v50, v58, v56
	v_mov_b64_e32 v[52:53], v[68:69]
	v_mov_b32_e32 v54, v61

.LBB0_595:
	s_andn2_b64 vcc, exec, s[0:1]
	v_mov_b64_e32 v[52:53], v[66:67]
	s_cbranch_vccnz .LBB0_597
	v_bfe_u32 v48, v49, 6, 6
	v_cndmask_b32_e64 v48, v152, v48, s[12:13]
	v_lshl_or_b32 v48, v48, 7, v67
	v_mov_b32_e32 v50, v51
	v_mov_b32_e32 v54, v55
	v_and_b32_e32 v48, 0xfdf, v49
	v_add_u32_e32 v48, 0x100, v48
	s_waitcnt vmcnt(22)
	v_mov_b32_e32 v52, v208
	v_mov_b32_e32 v53, v209
	v_pk_mul_f32 v[50:51], v[50:51], v[52:53] op_sel_hi:[0,1]
	v_pk_mul_f32 v[56:57], v[54:55], v[52:53] op_sel:[0,1] op_sel_hi:[0,0]
	v_pk_fma_f32 v[54:55], v[54:55], v[52:53], v[50:51] op_sel:[0,1,0] op_sel_hi:[0,0,1] neg_lo:[0,0,1] neg_hi:[0,0,1]
	v_add_f32_e32 v51, v56, v50
	v_mov_b64_e32 v[52:53], v[68:69]

.LBB0_599:
	s_andn2_b64 vcc, exec, s[0:1]
	v_mov_b64_e32 v[52:53], v[66:67]
	s_cbranch_vccnz .LBB0_601
	v_bfe_u32 v48, v49, 6, 6
	v_cndmask_b32_e64 v48, v150, v48, s[12:13]
	v_lshl_or_b32 v48, v48, 7, v67
	v_and_b32_e32 v48, 0xfec, v49
	v_add_u32_e32 v48, 0x100, v48
	s_waitcnt vmcnt(23)
	v_mov_b32_e32 v50, v210
	v_mov_b32_e32 v51, v211
	v_pk_mul_f32 v[52:53], v[40:41], v[50:51] op_sel_hi:[0,1]
	v_pk_mul_f32 v[54:55], v[44:45], v[50:51] op_sel:[0,1] op_sel_hi:[1,0]
	v_pk_fma_f32 v[50:51], v[44:45], v[50:51], v[52:53] op_sel:[0,1,0] op_sel_hi:[0,0,1] neg_lo:[0,0,1] neg_hi:[0,0,1]
	v_add_f32_e32 v50, v54, v52
	v_mov_b64_e32 v[52:53], v[68:69]

.LBB0_603:
	s_andn2_b64 vcc, exec, s[0:1]
	v_mov_b64_e32 v[50:51], v[66:67]
	s_cbranch_vccnz .LBB0_605
	v_bfe_u32 v48, v49, 6, 6
	v_cndmask_b32_e64 v48, v149, v48, s[12:13]
	v_lshl_or_b32 v48, v48, 7, v67
	v_and_b32_e32 v48, 0xfed, v49
	v_add_u32_e32 v48, 0x100, v48
	s_waitcnt vmcnt(24)
	v_mov_b32_e32 v50, v212
	v_mov_b32_e32 v51, v213
	v_pk_mul_f32 v[40:41], v[40:41], v[50:51] op_sel:[1,0]
	v_pk_mul_f32 v[52:53], v[44:45], v[50:51] op_sel:[1,1] op_sel_hi:[1,0]
	v_pk_fma_f32 v[44:45], v[44:45], v[50:51], v[40:41] op_sel:[1,1,0] op_sel_hi:[1,0,1] neg_lo:[0,0,1] neg_hi:[0,0,1]
	v_add_f32_e32 v41, v52, v40
	v_mov_b64_e32 v[50:51], v[68:69]

.LBB0_607:
	s_andn2_b64 vcc, exec, s[0:1]
	v_mov_b64_e32 v[44:45], v[66:67]
	s_cbranch_vccnz .LBB0_609
	v_bfe_u32 v40, v41, 6, 6
	v_cndmask_b32_e64 v40, v148, v40, s[12:13]
	v_lshl_or_b32 v40, v40, 7, v67
	v_and_b32_e32 v40, 0xfee, v41
	v_add_u32_e32 v40, 0x100, v40
	s_waitcnt vmcnt(25)
	v_mov_b32_e32 v44, v214
	v_mov_b32_e32 v45, v215
	v_pk_mul_f32 v[48:49], v[42:43], v[44:45] op_sel_hi:[0,1]
	v_pk_mul_f32 v[50:51], v[46:47], v[44:45] op_sel:[0,1] op_sel_hi:[1,0]
	v_pk_fma_f32 v[52:53], v[46:47], v[44:45], v[48:49] op_sel:[0,1,0] op_sel_hi:[0,0,1] neg_lo:[0,0,1] neg_hi:[0,0,1]
	v_add_f32_e32 v42, v50, v48
	v_mov_b64_e32 v[44:45], v[68:69]
	v_mov_b32_e32 v46, v53

.LBB0_611:
	s_andn2_b64 vcc, exec, s[0:1]
	v_mov_b64_e32 v[44:45], v[66:67]
	s_cbranch_vccnz .LBB0_613
	v_bfe_u32 v40, v41, 6, 6
	v_cndmask_b32_e64 v40, v147, v40, s[12:13]
	v_lshl_or_b32 v40, v40, 7, v67
	v_mov_b32_e32 v42, v43
	v_mov_b32_e32 v46, v47
	v_and_b32_e32 v40, 0xfef, v41
	v_add_u32_e32 v40, 0x100, v40
	s_waitcnt vmcnt(26)
	v_mov_b32_e32 v44, v216
	v_mov_b32_e32 v45, v217
	v_pk_mul_f32 v[42:43], v[42:43], v[44:45] op_sel_hi:[0,1]
	v_pk_mul_f32 v[48:49], v[46:47], v[44:45] op_sel:[0,1] op_sel_hi:[0,0]
	v_pk_fma_f32 v[46:47], v[46:47], v[44:45], v[42:43] op_sel:[0,1,0] op_sel_hi:[0,0,1] neg_lo:[0,0,1] neg_hi:[0,0,1]
	v_add_f32_e32 v43, v48, v42
	v_mov_b64_e32 v[44:45], v[68:69]

.LBB0_615:
	s_andn2_b64 vcc, exec, s[0:1]
	v_mov_b64_e32 v[44:45], v[66:67]
	s_cbranch_vccnz .LBB0_617
	v_bfe_u32 v40, v41, 6, 6
	v_cndmask_b32_e64 v40, v146, v40, s[12:13]
	v_lshl_or_b32 v40, v40, 7, v67
	v_and_b32_e32 v40, 0xffc, v41
	v_add_u32_e32 v40, 0x100, v40
	s_waitcnt vmcnt(27)
	v_mov_b32_e32 v42, v218
	v_mov_b32_e32 v43, v219
	v_pk_mul_f32 v[44:45], v[32:33], v[42:43] op_sel_hi:[0,1]
	v_pk_mul_f32 v[46:47], v[36:37], v[42:43] op_sel:[0,1] op_sel_hi:[1,0]
	v_pk_fma_f32 v[42:43], v[36:37], v[42:43], v[44:45] op_sel:[0,1,0] op_sel_hi:[0,0,1] neg_lo:[0,0,1] neg_hi:[0,0,1]
	v_add_f32_e32 v42, v46, v44
	v_mov_b64_e32 v[44:45], v[68:69]

.LBB0_619:
	s_andn2_b64 vcc, exec, s[0:1]
	v_mov_b64_e32 v[42:43], v[66:67]
	s_cbranch_vccnz .LBB0_621
	v_bfe_u32 v40, v41, 6, 6
	v_cndmask_b32_e64 v40, v145, v40, s[12:13]
	v_lshl_or_b32 v40, v40, 7, v67
	v_and_b32_e32 v40, 0xffd, v41
	v_add_u32_e32 v40, 0x100, v40
	s_waitcnt vmcnt(28)
	v_mov_b32_e32 v42, v220
	v_mov_b32_e32 v43, v221
	v_pk_mul_f32 v[32:33], v[32:33], v[42:43] op_sel:[1,0]
	v_pk_mul_f32 v[44:45], v[36:37], v[42:43] op_sel:[1,1] op_sel_hi:[1,0]
	v_pk_fma_f32 v[36:37], v[36:37], v[42:43], v[32:33] op_sel:[1,1,0] op_sel_hi:[1,0,1] neg_lo:[0,0,1] neg_hi:[0,0,1]
	v_add_f32_e32 v33, v44, v32
	v_mov_b64_e32 v[42:43], v[68:69]

.LBB0_623:
	s_andn2_b64 vcc, exec, s[0:1]
	v_mov_b64_e32 v[36:37], v[66:67]
	s_cbranch_vccnz .LBB0_625
	v_bfe_u32 v32, v33, 6, 6
	v_cndmask_b32_e64 v32, v144, v32, s[12:13]
	v_lshl_or_b32 v32, v32, 7, v67
	v_and_b32_e32 v32, 0xffe, v33
	v_add_u32_e32 v32, 0x100, v32
	s_waitcnt vmcnt(29)
	v_mov_b32_e32 v36, v222
	v_mov_b32_e32 v37, v223
	v_pk_mul_f32 v[40:41], v[34:35], v[36:37] op_sel_hi:[0,1]
	v_pk_mul_f32 v[42:43], v[38:39], v[36:37] op_sel:[0,1] op_sel_hi:[1,0]
	v_pk_fma_f32 v[44:45], v[38:39], v[36:37], v[40:41] op_sel:[0,1,0] op_sel_hi:[0,0,1] neg_lo:[0,0,1] neg_hi:[0,0,1]
	v_add_f32_e32 v34, v42, v40
	v_mov_b64_e32 v[36:37], v[68:69]
	v_mov_b32_e32 v38, v45

.LBB0_627:
	s_andn2_b64 vcc, exec, s[0:1]
	s_cbranch_vccnz .LBB0_629
	v_bfe_u32 v32, v33, 6, 6
	v_cndmask_b32_e64 v32, v135, v32, s[12:13]
	v_lshl_or_b32 v32, v32, 7, v67
	v_mov_b32_e32 v34, v35
	v_mov_b32_e32 v38, v39
	v_and_b32_e32 v32, 0xfff, v33
	v_add_u32_e32 v32, 0x100, v32
	v_mov_b64_e32 v[66:67], v[68:69]
	s_waitcnt vmcnt(30)
	v_mov_b32_e32 v36, v224
	v_mov_b32_e32 v37, v225
	v_pk_mul_f32 v[34:35], v[34:35], v[36:37] op_sel_hi:[0,1]
	v_pk_mul_f32 v[40:41], v[38:39], v[36:37] op_sel:[0,1] op_sel_hi:[0,0]
	v_pk_fma_f32 v[38:39], v[38:39], v[36:37], v[34:35] op_sel:[0,1,0] op_sel_hi:[0,0,1] neg_lo:[0,0,1] neg_hi:[0,0,1]
	v_add_f32_e32 v35, v40, v34
